# radix-select passes: 5-op bin index (xor/shift/min) instead of and/cmp/bfe/cndmask
# speedup vs baseline: 1.0138x; 1.0138x over previous
.LBB0_554:
	s_add_i32 s64, s50, -8
	s_lshl_b32 s50, -1, s50
	v_xor_b32_e32 v193, v192, v0
	s_waitcnt lgkmcnt(0)
	v_lshrrev_b32_e32 v193, s64, v193
	ds_write2st64_b32 v141, v209, v209 offset1:1
	ds_write2st64_b32 v141, v209, v209 offset0:2 offset1:3
	v_min_u32_e32 v193, v193, v142
	v_lshl_add_u32 v193, v193, 2, s85
	ds_add_u32 v193, v228
	v_xor_b32_e32 v193, v192, v1
	v_lshrrev_b32_e32 v193, s64, v193
	v_min_u32_e32 v193, v193, v142
	v_lshl_add_u32 v193, v193, 2, s85
	ds_add_u32 v193, v228
	v_xor_b32_e32 v193, v192, v2
	v_lshrrev_b32_e32 v193, s64, v193
	v_min_u32_e32 v193, v193, v142
	v_lshl_add_u32 v193, v193, 2, s85
	ds_add_u32 v193, v228
	v_xor_b32_e32 v193, v192, v3
	v_lshrrev_b32_e32 v193, s64, v193
	v_min_u32_e32 v193, v193, v142
	v_lshl_add_u32 v193, v193, 2, s85
	ds_add_u32 v193, v228
	s_cmp_le_u32 s98, 0
	s_cbranch_scc1 .Lsel_pa_end
	v_xor_b32_e32 v193, v192, v8
	v_lshrrev_b32_e32 v193, s64, v193
	v_min_u32_e32 v193, v193, v142
	v_lshl_add_u32 v193, v193, 2, s85
	ds_add_u32 v193, v228
	v_xor_b32_e32 v193, v192, v9
	v_lshrrev_b32_e32 v193, s64, v193
	v_min_u32_e32 v193, v193, v142
	v_lshl_add_u32 v193, v193, 2, s85
	ds_add_u32 v193, v228
	v_xor_b32_e32 v193, v192, v10
	v_lshrrev_b32_e32 v193, s64, v193
	v_min_u32_e32 v193, v193, v142
	v_lshl_add_u32 v193, v193, 2, s85
	ds_add_u32 v193, v228
	v_xor_b32_e32 v193, v192, v11
	v_lshrrev_b32_e32 v193, s64, v193
	v_min_u32_e32 v193, v193, v142
	v_lshl_add_u32 v193, v193, 2, s85
	ds_add_u32 v193, v228
	s_cmp_le_u32 s98, 1
	s_cbranch_scc1 .Lsel_pa_end
	v_xor_b32_e32 v193, v192, v4
	v_lshrrev_b32_e32 v193, s64, v193
	v_min_u32_e32 v193, v193, v142
	v_lshl_add_u32 v193, v193, 2, s85
	ds_add_u32 v193, v228
	v_xor_b32_e32 v193, v192, v5
	v_lshrrev_b32_e32 v193, s64, v193
	v_min_u32_e32 v193, v193, v142
	v_lshl_add_u32 v193, v193, 2, s85
	ds_add_u32 v193, v228
	v_xor_b32_e32 v193, v192, v6
	v_lshrrev_b32_e32 v193, s64, v193
	v_min_u32_e32 v193, v193, v142
	v_lshl_add_u32 v193, v193, 2, s85
	ds_add_u32 v193, v228
	v_xor_b32_e32 v193, v192, v7
	v_lshrrev_b32_e32 v193, s64, v193
	v_min_u32_e32 v193, v193, v142
	v_lshl_add_u32 v193, v193, 2, s85
	ds_add_u32 v193, v228
	s_cmp_le_u32 s98, 2
	s_cbranch_scc1 .Lsel_pa_end
	v_xor_b32_e32 v193, v192, v12
	v_lshrrev_b32_e32 v193, s64, v193
	v_min_u32_e32 v193, v193, v142
	v_lshl_add_u32 v193, v193, 2, s85
	ds_add_u32 v193, v228
	v_xor_b32_e32 v193, v192, v13
	v_lshrrev_b32_e32 v193, s64, v193
	v_min_u32_e32 v193, v193, v142
	v_lshl_add_u32 v193, v193, 2, s85
	ds_add_u32 v193, v228
	v_xor_b32_e32 v193, v192, v14
	v_lshrrev_b32_e32 v193, s64, v193
	v_min_u32_e32 v193, v193, v142
	v_lshl_add_u32 v193, v193, 2, s85
	ds_add_u32 v193, v228
	v_xor_b32_e32 v193, v192, v15
	v_lshrrev_b32_e32 v193, s64, v193
	v_min_u32_e32 v193, v193, v142
	v_lshl_add_u32 v193, v193, 2, s85
	ds_add_u32 v193, v228
	s_cmp_le_u32 s98, 3
	s_cbranch_scc1 .Lsel_pa_end
	v_xor_b32_e32 v193, v192, v16
	v_lshrrev_b32_e32 v193, s64, v193
	v_min_u32_e32 v193, v193, v142
	v_lshl_add_u32 v193, v193, 2, s85
	ds_add_u32 v193, v228
	v_xor_b32_e32 v193, v192, v17
	v_lshrrev_b32_e32 v193, s64, v193
	v_min_u32_e32 v193, v193, v142
	v_lshl_add_u32 v193, v193, 2, s85
	ds_add_u32 v193, v228
	v_xor_b32_e32 v193, v192, v18
	v_lshrrev_b32_e32 v193, s64, v193
	v_min_u32_e32 v193, v193, v142
	v_lshl_add_u32 v193, v193, 2, s85
	ds_add_u32 v193, v228
	v_xor_b32_e32 v193, v192, v19
	v_lshrrev_b32_e32 v193, s64, v193
	v_min_u32_e32 v193, v193, v142
	v_lshl_add_u32 v193, v193, 2, s85
	ds_add_u32 v193, v228
	s_cmp_le_u32 s98, 4
	s_cbranch_scc1 .Lsel_pa_end
	v_xor_b32_e32 v193, v192, v24
	v_lshrrev_b32_e32 v193, s64, v193
	v_min_u32_e32 v193, v193, v142
	v_lshl_add_u32 v193, v193, 2, s85
	ds_add_u32 v193, v228
	v_xor_b32_e32 v193, v192, v25
	v_lshrrev_b32_e32 v193, s64, v193
	v_min_u32_e32 v193, v193, v142
	v_lshl_add_u32 v193, v193, 2, s85
	ds_add_u32 v193, v228
	v_xor_b32_e32 v193, v192, v26
	v_lshrrev_b32_e32 v193, s64, v193
	v_min_u32_e32 v193, v193, v142
	v_lshl_add_u32 v193, v193, 2, s85
	ds_add_u32 v193, v228
	v_xor_b32_e32 v193, v192, v27
	v_lshrrev_b32_e32 v193, s64, v193
	v_min_u32_e32 v193, v193, v142
	v_lshl_add_u32 v193, v193, 2, s85
	ds_add_u32 v193, v228
	s_cmp_le_u32 s98, 5
	s_cbranch_scc1 .Lsel_pa_end
	v_xor_b32_e32 v193, v192, v20
	v_lshrrev_b32_e32 v193, s64, v193
	v_min_u32_e32 v193, v193, v142
	v_lshl_add_u32 v193, v193, 2, s85
	ds_add_u32 v193, v228
	v_xor_b32_e32 v193, v192, v21
	v_lshrrev_b32_e32 v193, s64, v193
	v_min_u32_e32 v193, v193, v142
	v_lshl_add_u32 v193, v193, 2, s85
	ds_add_u32 v193, v228
	v_xor_b32_e32 v193, v192, v22
	v_lshrrev_b32_e32 v193, s64, v193
	v_min_u32_e32 v193, v193, v142
	v_lshl_add_u32 v193, v193, 2, s85
	ds_add_u32 v193, v228
	v_xor_b32_e32 v193, v192, v23
	v_lshrrev_b32_e32 v193, s64, v193
	v_min_u32_e32 v193, v193, v142
	v_lshl_add_u32 v193, v193, 2, s85
	ds_add_u32 v193, v228
	s_cmp_le_u32 s98, 6
	s_cbranch_scc1 .Lsel_pa_end
	v_xor_b32_e32 v193, v192, v32
	v_lshrrev_b32_e32 v193, s64, v193
	v_min_u32_e32 v193, v193, v142
	v_lshl_add_u32 v193, v193, 2, s85
	ds_add_u32 v193, v228
	v_xor_b32_e32 v193, v192, v33
	v_lshrrev_b32_e32 v193, s64, v193
	v_min_u32_e32 v193, v193, v142
	v_lshl_add_u32 v193, v193, 2, s85
	ds_add_u32 v193, v228
	v_xor_b32_e32 v193, v192, v34
	v_lshrrev_b32_e32 v193, s64, v193
	v_min_u32_e32 v193, v193, v142
	v_lshl_add_u32 v193, v193, 2, s85
	ds_add_u32 v193, v228
	v_xor_b32_e32 v193, v192, v35
	v_lshrrev_b32_e32 v193, s64, v193
	v_min_u32_e32 v193, v193, v142
	v_lshl_add_u32 v193, v193, 2, s85
	ds_add_u32 v193, v228
	s_cmp_le_u32 s98, 7
	s_cbranch_scc1 .Lsel_pa_end
	v_xor_b32_e32 v193, v192, v28
	v_lshrrev_b32_e32 v193, s64, v193
	v_min_u32_e32 v193, v193, v142
	v_lshl_add_u32 v193, v193, 2, s85
	ds_add_u32 v193, v228
	v_xor_b32_e32 v193, v192, v29
	v_lshrrev_b32_e32 v193, s64, v193
	v_min_u32_e32 v193, v193, v142
	v_lshl_add_u32 v193, v193, 2, s85
	ds_add_u32 v193, v228
	v_xor_b32_e32 v193, v192, v30
	v_lshrrev_b32_e32 v193, s64, v193
	v_min_u32_e32 v193, v193, v142
	v_lshl_add_u32 v193, v193, 2, s85
	ds_add_u32 v193, v228
	v_xor_b32_e32 v193, v192, v31
	v_lshrrev_b32_e32 v193, s64, v193
	v_min_u32_e32 v193, v193, v142
	v_lshl_add_u32 v193, v193, 2, s85
	ds_add_u32 v193, v228
	s_cmp_le_u32 s98, 8
	s_cbranch_scc1 .Lsel_pa_end
	v_xor_b32_e32 v193, v192, v40
	v_lshrrev_b32_e32 v193, s64, v193
	v_min_u32_e32 v193, v193, v142
	v_lshl_add_u32 v193, v193, 2, s85
	ds_add_u32 v193, v228
	v_xor_b32_e32 v193, v192, v41
	v_lshrrev_b32_e32 v193, s64, v193
	v_min_u32_e32 v193, v193, v142
	v_lshl_add_u32 v193, v193, 2, s85
	ds_add_u32 v193, v228
	v_xor_b32_e32 v193, v192, v42
	v_lshrrev_b32_e32 v193, s64, v193
	v_min_u32_e32 v193, v193, v142
	v_lshl_add_u32 v193, v193, 2, s85
	ds_add_u32 v193, v228
	v_xor_b32_e32 v193, v192, v43
	v_lshrrev_b32_e32 v193, s64, v193
	v_min_u32_e32 v193, v193, v142
	v_lshl_add_u32 v193, v193, 2, s85
	ds_add_u32 v193, v228
	s_cmp_le_u32 s98, 9
	s_cbranch_scc1 .Lsel_pa_end
	v_xor_b32_e32 v193, v192, v36
	v_lshrrev_b32_e32 v193, s64, v193
	v_min_u32_e32 v193, v193, v142
	v_lshl_add_u32 v193, v193, 2, s85
	ds_add_u32 v193, v228
	v_xor_b32_e32 v193, v192, v37
	v_lshrrev_b32_e32 v193, s64, v193
	v_min_u32_e32 v193, v193, v142
	v_lshl_add_u32 v193, v193, 2, s85
	ds_add_u32 v193, v228
	v_xor_b32_e32 v193, v192, v38
	v_lshrrev_b32_e32 v193, s64, v193
	v_min_u32_e32 v193, v193, v142
	v_lshl_add_u32 v193, v193, 2, s85
	ds_add_u32 v193, v228
	v_xor_b32_e32 v193, v192, v39
	v_lshrrev_b32_e32 v193, s64, v193
	v_min_u32_e32 v193, v193, v142
	v_lshl_add_u32 v193, v193, 2, s85
	ds_add_u32 v193, v228
	s_cmp_le_u32 s98, 10
	s_cbranch_scc1 .Lsel_pa_end
	v_xor_b32_e32 v193, v192, v48
	v_lshrrev_b32_e32 v193, s64, v193
	v_min_u32_e32 v193, v193, v142
	v_lshl_add_u32 v193, v193, 2, s85
	ds_add_u32 v193, v228
	v_xor_b32_e32 v193, v192, v49
	v_lshrrev_b32_e32 v193, s64, v193
	v_min_u32_e32 v193, v193, v142
	v_lshl_add_u32 v193, v193, 2, s85
	ds_add_u32 v193, v228
	v_xor_b32_e32 v193, v192, v50
	v_lshrrev_b32_e32 v193, s64, v193
	v_min_u32_e32 v193, v193, v142
	v_lshl_add_u32 v193, v193, 2, s85
	ds_add_u32 v193, v228
	v_xor_b32_e32 v193, v192, v51
	v_lshrrev_b32_e32 v193, s64, v193
	v_min_u32_e32 v193, v193, v142
	v_lshl_add_u32 v193, v193, 2, s85
	ds_add_u32 v193, v228
	s_cmp_le_u32 s98, 11
	s_cbranch_scc1 .Lsel_pa_end
	v_xor_b32_e32 v193, v192, v44
	v_lshrrev_b32_e32 v193, s64, v193
	v_min_u32_e32 v193, v193, v142
	v_lshl_add_u32 v193, v193, 2, s85
	ds_add_u32 v193, v228
	v_xor_b32_e32 v193, v192, v45
	v_lshrrev_b32_e32 v193, s64, v193
	v_min_u32_e32 v193, v193, v142
	v_lshl_add_u32 v193, v193, 2, s85
	ds_add_u32 v193, v228
	v_xor_b32_e32 v193, v192, v46
	v_lshrrev_b32_e32 v193, s64, v193
	v_min_u32_e32 v193, v193, v142
	v_lshl_add_u32 v193, v193, 2, s85
	ds_add_u32 v193, v228
	v_xor_b32_e32 v193, v192, v47
	v_lshrrev_b32_e32 v193, s64, v193
	v_min_u32_e32 v193, v193, v142
	v_lshl_add_u32 v193, v193, 2, s85
	ds_add_u32 v193, v228
	s_cmp_le_u32 s98, 12
	s_cbranch_scc1 .Lsel_pa_end
	v_xor_b32_e32 v193, v192, v56
	v_lshrrev_b32_e32 v193, s64, v193
	v_min_u32_e32 v193, v193, v142
	v_lshl_add_u32 v193, v193, 2, s85
	ds_add_u32 v193, v228
	v_xor_b32_e32 v193, v192, v57
	v_lshrrev_b32_e32 v193, s64, v193
	v_min_u32_e32 v193, v193, v142
	v_lshl_add_u32 v193, v193, 2, s85
	ds_add_u32 v193, v228
	v_xor_b32_e32 v193, v192, v58
	v_lshrrev_b32_e32 v193, s64, v193
	v_min_u32_e32 v193, v193, v142
	v_lshl_add_u32 v193, v193, 2, s85
	ds_add_u32 v193, v228
	v_xor_b32_e32 v193, v192, v59
	v_lshrrev_b32_e32 v193, s64, v193
	v_min_u32_e32 v193, v193, v142
	v_lshl_add_u32 v193, v193, 2, s85
	ds_add_u32 v193, v228
	s_cmp_le_u32 s98, 13
	s_cbranch_scc1 .Lsel_pa_end
	v_xor_b32_e32 v193, v192, v52
	v_lshrrev_b32_e32 v193, s64, v193
	v_min_u32_e32 v193, v193, v142
	v_lshl_add_u32 v193, v193, 2, s85
	ds_add_u32 v193, v228
	v_xor_b32_e32 v193, v192, v53
	v_lshrrev_b32_e32 v193, s64, v193
	v_min_u32_e32 v193, v193, v142
	v_lshl_add_u32 v193, v193, 2, s85
	ds_add_u32 v193, v228
	v_xor_b32_e32 v193, v192, v54
	v_lshrrev_b32_e32 v193, s64, v193
	v_min_u32_e32 v193, v193, v142
	v_lshl_add_u32 v193, v193, 2, s85
	ds_add_u32 v193, v228
	v_xor_b32_e32 v193, v192, v55
	v_lshrrev_b32_e32 v193, s64, v193
	v_min_u32_e32 v193, v193, v142
	v_lshl_add_u32 v193, v193, 2, s85
	ds_add_u32 v193, v228
	s_cmp_le_u32 s98, 14
	s_cbranch_scc1 .Lsel_pa_end
	v_xor_b32_e32 v193, v192, v60
	v_lshrrev_b32_e32 v193, s64, v193
	v_min_u32_e32 v193, v193, v142
	v_lshl_add_u32 v193, v193, 2, s85
	ds_add_u32 v193, v228
	v_xor_b32_e32 v193, v192, v61
	v_lshrrev_b32_e32 v193, s64, v193
	v_min_u32_e32 v193, v193, v142
	v_lshl_add_u32 v193, v193, 2, s85
	ds_add_u32 v193, v228
	v_xor_b32_e32 v193, v192, v62
	v_lshrrev_b32_e32 v193, s64, v193
	v_min_u32_e32 v193, v193, v142
	v_lshl_add_u32 v193, v193, 2, s85
	ds_add_u32 v193, v228
	v_xor_b32_e32 v193, v192, v63
	v_lshrrev_b32_e32 v193, s64, v193
	v_min_u32_e32 v193, v193, v142
	v_lshl_add_u32 v193, v193, 2, s85
	ds_add_u32 v193, v228

.LBB0_662:
	s_add_i32 s64, s50, -8
	s_lshl_b32 s50, -1, s50
	v_xor_b32_e32 v65, v95, v239
	s_waitcnt lgkmcnt(0)
	v_lshrrev_b32_e32 v65, s64, v65
	ds_write2st64_b32 v141, v209, v209 offset1:1
	ds_write2st64_b32 v141, v209, v209 offset0:2 offset1:3
	v_min_u32_e32 v65, v65, v142
	v_lshl_add_u32 v65, v65, 2, s85
	ds_add_u32 v65, v228
	v_xor_b32_e32 v65, v95, v240
	v_lshrrev_b32_e32 v65, s64, v65
	v_min_u32_e32 v65, v65, v142
	v_lshl_add_u32 v65, v65, 2, s85
	ds_add_u32 v65, v228
	v_xor_b32_e32 v65, v95, v238
	v_lshrrev_b32_e32 v65, s64, v65
	v_min_u32_e32 v65, v65, v142
	v_lshl_add_u32 v65, v65, 2, s85
	ds_add_u32 v65, v228
	v_xor_b32_e32 v65, v95, v237
	v_lshrrev_b32_e32 v65, s64, v65
	v_min_u32_e32 v65, v65, v142
	v_lshl_add_u32 v65, v65, 2, s85
	ds_add_u32 v65, v228
	s_cmp_le_u32 s98, 0
	s_cbranch_scc1 .Lsel_pb_end
	v_xor_b32_e32 v65, v95, v235
	v_lshrrev_b32_e32 v65, s64, v65
	v_min_u32_e32 v65, v65, v142
	v_lshl_add_u32 v65, v65, 2, s85
	ds_add_u32 v65, v228
	v_xor_b32_e32 v65, v95, v236
	v_lshrrev_b32_e32 v65, s64, v65
	v_min_u32_e32 v65, v65, v142
	v_lshl_add_u32 v65, v65, 2, s85
	ds_add_u32 v65, v228
	v_xor_b32_e32 v65, v95, v234
	v_lshrrev_b32_e32 v65, s64, v65
	v_min_u32_e32 v65, v65, v142
	v_lshl_add_u32 v65, v65, 2, s85
	ds_add_u32 v65, v228
	v_xor_b32_e32 v65, v95, v233
	v_lshrrev_b32_e32 v65, s64, v65
	v_min_u32_e32 v65, v65, v142
	v_lshl_add_u32 v65, v65, 2, s85
	ds_add_u32 v65, v228
	s_cmp_le_u32 s98, 1
	s_cbranch_scc1 .Lsel_pb_end
	v_xor_b32_e32 v65, v95, v213
	v_lshrrev_b32_e32 v65, s64, v65
	v_min_u32_e32 v65, v65, v142
	v_lshl_add_u32 v65, v65, 2, s85
	ds_add_u32 v65, v228
	v_xor_b32_e32 v65, v95, v232
	v_lshrrev_b32_e32 v65, s64, v65
	v_min_u32_e32 v65, v65, v142
	v_lshl_add_u32 v65, v65, 2, s85
	ds_add_u32 v65, v228
	v_xor_b32_e32 v65, v95, v212
	v_lshrrev_b32_e32 v65, s64, v65
	v_min_u32_e32 v65, v65, v142
	v_lshl_add_u32 v65, v65, 2, s85
	ds_add_u32 v65, v228
	v_xor_b32_e32 v65, v95, v211
	v_lshrrev_b32_e32 v65, s64, v65
	v_min_u32_e32 v65, v65, v142
	v_lshl_add_u32 v65, v65, 2, s85
	ds_add_u32 v65, v228
	s_cmp_le_u32 s98, 2
	s_cbranch_scc1 .Lsel_pb_end
	v_xor_b32_e32 v65, v95, v207
	v_lshrrev_b32_e32 v65, s64, v65
	v_min_u32_e32 v65, v65, v142
	v_lshl_add_u32 v65, v65, 2, s85
	ds_add_u32 v65, v228
	v_xor_b32_e32 v65, v95, v210
	v_lshrrev_b32_e32 v65, s64, v65
	v_min_u32_e32 v65, v65, v142
	v_lshl_add_u32 v65, v65, 2, s85
	ds_add_u32 v65, v228
	v_xor_b32_e32 v65, v95, v206
	v_lshrrev_b32_e32 v65, s64, v65
	v_min_u32_e32 v65, v65, v142
	v_lshl_add_u32 v65, v65, 2, s85
	ds_add_u32 v65, v228
	v_xor_b32_e32 v65, v95, v205
	v_lshrrev_b32_e32 v65, s64, v65
	v_min_u32_e32 v65, v65, v142
	v_lshl_add_u32 v65, v65, 2, s85
	ds_add_u32 v65, v228
	s_cmp_le_u32 s98, 3
	s_cbranch_scc1 .Lsel_pb_end
	v_xor_b32_e32 v65, v95, v203
	v_lshrrev_b32_e32 v65, s64, v65
	v_min_u32_e32 v65, v65, v142
	v_lshl_add_u32 v65, v65, 2, s85
	ds_add_u32 v65, v228
	v_xor_b32_e32 v65, v95, v204
	v_lshrrev_b32_e32 v65, s64, v65
	v_min_u32_e32 v65, v65, v142
	v_lshl_add_u32 v65, v65, 2, s85
	ds_add_u32 v65, v228
	v_xor_b32_e32 v65, v95, v202
	v_lshrrev_b32_e32 v65, s64, v65
	v_min_u32_e32 v65, v65, v142
	v_lshl_add_u32 v65, v65, 2, s85
	ds_add_u32 v65, v228
	v_xor_b32_e32 v65, v95, v201
	v_lshrrev_b32_e32 v65, s64, v65
	v_min_u32_e32 v65, v65, v142
	v_lshl_add_u32 v65, v65, 2, s85
	ds_add_u32 v65, v228
	s_cmp_le_u32 s98, 4
	s_cbranch_scc1 .Lsel_pb_end
	v_xor_b32_e32 v65, v95, v199
	v_lshrrev_b32_e32 v65, s64, v65
	v_min_u32_e32 v65, v65, v142
	v_lshl_add_u32 v65, v65, 2, s85
	ds_add_u32 v65, v228
	v_xor_b32_e32 v65, v95, v200
	v_lshrrev_b32_e32 v65, s64, v65
	v_min_u32_e32 v65, v65, v142
	v_lshl_add_u32 v65, v65, 2, s85
	ds_add_u32 v65, v228
	v_xor_b32_e32 v65, v95, v198
	v_lshrrev_b32_e32 v65, s64, v65
	v_min_u32_e32 v65, v65, v142
	v_lshl_add_u32 v65, v65, 2, s85
	ds_add_u32 v65, v228
	v_xor_b32_e32 v65, v95, v197
	v_lshrrev_b32_e32 v65, s64, v65
	v_min_u32_e32 v65, v65, v142
	v_lshl_add_u32 v65, v65, 2, s85
	ds_add_u32 v65, v228
	s_cmp_le_u32 s98, 5
	s_cbranch_scc1 .Lsel_pb_end
	v_xor_b32_e32 v65, v95, v195
	v_lshrrev_b32_e32 v65, s64, v65
	v_min_u32_e32 v65, v65, v142
	v_lshl_add_u32 v65, v65, 2, s85
	ds_add_u32 v65, v228
	v_xor_b32_e32 v65, v95, v196
	v_lshrrev_b32_e32 v65, s64, v65
	v_min_u32_e32 v65, v65, v142
	v_lshl_add_u32 v65, v65, 2, s85
	ds_add_u32 v65, v228
	v_xor_b32_e32 v65, v95, v194
	v_lshrrev_b32_e32 v65, s64, v65
	v_min_u32_e32 v65, v65, v142
	v_lshl_add_u32 v65, v65, 2, s85
	ds_add_u32 v65, v228
	v_xor_b32_e32 v65, v95, v193
	v_lshrrev_b32_e32 v65, s64, v65
	v_min_u32_e32 v65, v65, v142
	v_lshl_add_u32 v65, v65, 2, s85
	ds_add_u32 v65, v228
	s_cmp_le_u32 s98, 6
	s_cbranch_scc1 .Lsel_pb_end
	v_xor_b32_e32 v65, v95, v137
	v_lshrrev_b32_e32 v65, s64, v65
	v_min_u32_e32 v65, v65, v142
	v_lshl_add_u32 v65, v65, 2, s85
	ds_add_u32 v65, v228
	v_xor_b32_e32 v65, v95, v192
	v_lshrrev_b32_e32 v65, s64, v65
	v_min_u32_e32 v65, v65, v142
	v_lshl_add_u32 v65, v65, 2, s85
	ds_add_u32 v65, v228
	v_xor_b32_e32 v65, v95, v136
	v_lshrrev_b32_e32 v65, s64, v65
	v_min_u32_e32 v65, v65, v142
	v_lshl_add_u32 v65, v65, 2, s85
	ds_add_u32 v65, v228
	v_xor_b32_e32 v65, v95, v99
	v_lshrrev_b32_e32 v65, s64, v65
	v_min_u32_e32 v65, v65, v142
	v_lshl_add_u32 v65, v65, 2, s85
	ds_add_u32 v65, v228
	s_cmp_le_u32 s98, 7
	s_cbranch_scc1 .Lsel_pb_end
	v_xor_b32_e32 v65, v95, v97
	v_lshrrev_b32_e32 v65, s64, v65
	v_min_u32_e32 v65, v65, v142
	v_lshl_add_u32 v65, v65, 2, s85
	ds_add_u32 v65, v228
	v_xor_b32_e32 v65, v95, v98
	v_lshrrev_b32_e32 v65, s64, v65
	v_min_u32_e32 v65, v65, v142
	v_lshl_add_u32 v65, v65, 2, s85
	ds_add_u32 v65, v228
	v_xor_b32_e32 v65, v95, v96
	v_lshrrev_b32_e32 v65, s64, v65
	v_min_u32_e32 v65, v65, v142
	v_lshl_add_u32 v65, v65, 2, s85
	ds_add_u32 v65, v228
	v_xor_b32_e32 v65, v95, v94
	v_lshrrev_b32_e32 v65, s64, v65
	v_min_u32_e32 v65, v65, v142
	v_lshl_add_u32 v65, v65, 2, s85
	ds_add_u32 v65, v228
	s_cmp_le_u32 s98, 8
	s_cbranch_scc1 .Lsel_pb_end
	v_xor_b32_e32 v65, v95, v92
	v_lshrrev_b32_e32 v65, s64, v65
	v_min_u32_e32 v65, v65, v142
	v_lshl_add_u32 v65, v65, 2, s85
	ds_add_u32 v65, v228
	v_xor_b32_e32 v65, v95, v93
	v_lshrrev_b32_e32 v65, s64, v65
	v_min_u32_e32 v65, v65, v142
	v_lshl_add_u32 v65, v65, 2, s85
	ds_add_u32 v65, v228
	v_xor_b32_e32 v65, v95, v91
	v_lshrrev_b32_e32 v65, s64, v65
	v_min_u32_e32 v65, v65, v142
	v_lshl_add_u32 v65, v65, 2, s85
	ds_add_u32 v65, v228
	v_xor_b32_e32 v65, v95, v90
	v_lshrrev_b32_e32 v65, s64, v65
	v_min_u32_e32 v65, v65, v142
	v_lshl_add_u32 v65, v65, 2, s85
	ds_add_u32 v65, v228
	s_cmp_le_u32 s98, 9
	s_cbranch_scc1 .Lsel_pb_end
	v_xor_b32_e32 v65, v95, v88
	v_lshrrev_b32_e32 v65, s64, v65
	v_min_u32_e32 v65, v65, v142
	v_lshl_add_u32 v65, v65, 2, s85
	ds_add_u32 v65, v228
	v_xor_b32_e32 v65, v95, v89
	v_lshrrev_b32_e32 v65, s64, v65
	v_min_u32_e32 v65, v65, v142
	v_lshl_add_u32 v65, v65, 2, s85
	ds_add_u32 v65, v228
	v_xor_b32_e32 v65, v95, v87
	v_lshrrev_b32_e32 v65, s64, v65
	v_min_u32_e32 v65, v65, v142
	v_lshl_add_u32 v65, v65, 2, s85
	ds_add_u32 v65, v228
	v_xor_b32_e32 v65, v95, v86
	v_lshrrev_b32_e32 v65, s64, v65
	v_min_u32_e32 v65, v65, v142
	v_lshl_add_u32 v65, v65, 2, s85
	ds_add_u32 v65, v228
	s_cmp_le_u32 s98, 10
	s_cbranch_scc1 .Lsel_pb_end
	v_xor_b32_e32 v65, v95, v84
	v_lshrrev_b32_e32 v65, s64, v65
	v_min_u32_e32 v65, v65, v142
	v_lshl_add_u32 v65, v65, 2, s85
	ds_add_u32 v65, v228
	v_xor_b32_e32 v65, v95, v85
	v_lshrrev_b32_e32 v65, s64, v65
	v_min_u32_e32 v65, v65, v142
	v_lshl_add_u32 v65, v65, 2, s85
	ds_add_u32 v65, v228
	v_xor_b32_e32 v65, v95, v83
	v_lshrrev_b32_e32 v65, s64, v65
	v_min_u32_e32 v65, v65, v142
	v_lshl_add_u32 v65, v65, 2, s85
	ds_add_u32 v65, v228
	v_xor_b32_e32 v65, v95, v82
	v_lshrrev_b32_e32 v65, s64, v65
	v_min_u32_e32 v65, v65, v142
	v_lshl_add_u32 v65, v65, 2, s85
	ds_add_u32 v65, v228
	s_cmp_le_u32 s98, 11
	s_cbranch_scc1 .Lsel_pb_end
	v_xor_b32_e32 v65, v95, v80
	v_lshrrev_b32_e32 v65, s64, v65
	v_min_u32_e32 v65, v65, v142
	v_lshl_add_u32 v65, v65, 2, s85
	ds_add_u32 v65, v228
	v_xor_b32_e32 v65, v95, v81
	v_lshrrev_b32_e32 v65, s64, v65
	v_min_u32_e32 v65, v65, v142
	v_lshl_add_u32 v65, v65, 2, s85
	ds_add_u32 v65, v228
	v_xor_b32_e32 v65, v95, v79
	v_lshrrev_b32_e32 v65, s64, v65
	v_min_u32_e32 v65, v65, v142
	v_lshl_add_u32 v65, v65, 2, s85
	ds_add_u32 v65, v228
	v_xor_b32_e32 v65, v95, v78
	v_lshrrev_b32_e32 v65, s64, v65
	v_min_u32_e32 v65, v65, v142
	v_lshl_add_u32 v65, v65, 2, s85
	ds_add_u32 v65, v228
	s_cmp_le_u32 s98, 12
	s_cbranch_scc1 .Lsel_pb_end
	v_xor_b32_e32 v65, v95, v76
	v_lshrrev_b32_e32 v65, s64, v65
	v_min_u32_e32 v65, v65, v142
	v_lshl_add_u32 v65, v65, 2, s85
	ds_add_u32 v65, v228
	v_xor_b32_e32 v65, v95, v77
	v_lshrrev_b32_e32 v65, s64, v65
	v_min_u32_e32 v65, v65, v142
	v_lshl_add_u32 v65, v65, 2, s85
	ds_add_u32 v65, v228
	v_xor_b32_e32 v65, v95, v75
	v_lshrrev_b32_e32 v65, s64, v65
	v_min_u32_e32 v65, v65, v142
	v_lshl_add_u32 v65, v65, 2, s85
	ds_add_u32 v65, v228
	v_xor_b32_e32 v65, v95, v74
	v_lshrrev_b32_e32 v65, s64, v65
	v_min_u32_e32 v65, v65, v142
	v_lshl_add_u32 v65, v65, 2, s85
	ds_add_u32 v65, v228
	s_cmp_le_u32 s98, 13
	s_cbranch_scc1 .Lsel_pb_end
	v_xor_b32_e32 v65, v95, v72
	v_lshrrev_b32_e32 v65, s64, v65
	v_min_u32_e32 v65, v65, v142
	v_lshl_add_u32 v65, v65, 2, s85
	ds_add_u32 v65, v228
	v_xor_b32_e32 v65, v95, v73
	v_lshrrev_b32_e32 v65, s64, v65
	v_min_u32_e32 v65, v65, v142
	v_lshl_add_u32 v65, v65, 2, s85
	ds_add_u32 v65, v228
	v_xor_b32_e32 v65, v95, v71
	v_lshrrev_b32_e32 v65, s64, v65
	v_min_u32_e32 v65, v65, v142
	v_lshl_add_u32 v65, v65, 2, s85
	ds_add_u32 v65, v228
	v_xor_b32_e32 v65, v95, v70
	v_lshrrev_b32_e32 v65, s64, v65
	v_min_u32_e32 v65, v65, v142
	v_lshl_add_u32 v65, v65, 2, s85
	ds_add_u32 v65, v228
	s_cmp_le_u32 s98, 14
	s_cbranch_scc1 .Lsel_pb_end
	v_xor_b32_e32 v65, v95, v67
	v_lshrrev_b32_e32 v65, s64, v65
	v_min_u32_e32 v65, v65, v142
	v_lshl_add_u32 v65, v65, 2, s85
	ds_add_u32 v65, v228
	v_xor_b32_e32 v65, v95, v68
	v_lshrrev_b32_e32 v65, s64, v65
	v_min_u32_e32 v65, v65, v142
	v_lshl_add_u32 v65, v65, 2, s85
	ds_add_u32 v65, v228
	v_xor_b32_e32 v65, v95, v66
	v_lshrrev_b32_e32 v65, s64, v65
	v_min_u32_e32 v65, v65, v142
	v_lshl_add_u32 v65, v65, 2, s85
	ds_add_u32 v65, v228
	v_xor_b32_e32 v65, v95, v69
	v_lshrrev_b32_e32 v65, s64, v65
	v_min_u32_e32 v65, v65, v142
	v_lshl_add_u32 v65, v65, 2, s85
	ds_add_u32 v65, v228
